# v011 + early L2 write-back by non-leader workgroups inside the grid barrier
# baseline (speedup 1.0000x reference)
; __device__ __forceinline__ unsigned xb_ld(unsigned* p)              { return __hip_atomic_load(p, __ATOMIC_RELAXED, __HIP_MEMORY_SCOPE_AGENT); }
; __device__ __forceinline__ unsigned xb_add(unsigned* p, unsigned v) { return __hip_atomic_fetch_add(p, v, __ATOMIC_RELAXED, __HIP_MEMORY_SCOPE_AGENT); }
; #define XB_SPIN(cond, bar) do { unsigned _sp = 0; while (cond) { __builtin_amdgcn_s_sleep(1); \
;     if ((++_sp & 255u) == 0u) { if (xb_ld(&(bar)[XB_TMO])) break; if (_sp > XB_SPIN_CAP) { atomicAdd(&(bar)[XB_TMO], 1u); break; } } } } while (0)
; __device__ __forceinline__ void xcd_barrier(const XcdBarrier& b) {
;     ...
;         const unsigned old = xb_add(&bar[XB_XSUB(b.x)], 1u);
;         const unsigned gen = old / nloc;
;         if (old + 1u == (gen + 1u) * nloc) {
;             __builtin_amdgcn_fence(__ATOMIC_RELEASE, "agent");
;             asm volatile("s_waitcnt vmcnt(0)" ::: "memory");
;             const unsigned og = xb_add(&bar[XB_TOP], 1u);
;             const unsigned tg = og / nx;
;             if (og + 1u == (tg + 1u) * nx) xb_add(&bar[XB_TOPGEN], 1u);
;             else XB_SPIN(xb_ld(&bar[XB_TOPGEN]) == tg, bar);
;             __builtin_amdgcn_fence(__ATOMIC_ACQUIRE, "agent");
;             xb_add(&bar[XB_XGEN(b.x)], 1u);
;             asm volatile("s_waitcnt vmcnt(0)" ::: "memory");
;         } else {
;             XB_SPIN(xb_ld(&bar[XB_XGEN(b.x)]) == gen, bar);
;             __builtin_amdgcn_fence(__ATOMIC_ACQUIRE, "agent");
;             asm volatile("s_waitcnt vmcnt(0)" ::: "memory");
;         }
.LBB0_226:
	s_or_b64 exec, exec, s[10:11]
	v_cvt_f32_u32_e32 v4, v2
	s_waitcnt vmcnt(0)
	v_readfirstlane_b32 s0, v3
	v_sub_u32_e32 v3, 0, v2
	v_rcp_iflag_f32_e32 v4, v4
	v_add_u32_e32 v5, s0, v1
	v_mul_f32_e32 v4, 0x4f7ffffe, v4
	v_cvt_u32_f32_e32 v4, v4
	v_mul_lo_u32 v1, v3, v4
	v_mul_hi_u32 v1, v4, v1
	v_add_u32_e32 v1, v4, v1
	v_mul_hi_u32 v1, v5, v1
	v_mul_lo_u32 v3, v1, v2
	v_sub_u32_e32 v3, v5, v3
	v_add_u32_e32 v4, 1, v1
	v_cmp_ge_u32_e32 vcc, v3, v2
	s_nop 1
	v_cndmask_b32_e32 v1, v1, v4, vcc
	v_sub_u32_e32 v4, v3, v2
	v_cndmask_b32_e32 v3, v3, v4, vcc
	v_add_u32_e32 v4, 1, v1
	v_cmp_ge_u32_e32 vcc, v3, v2
	v_add_u32_e32 v3, 1, v5
	s_nop 0
	v_cndmask_b32_e32 v1, v1, v4, vcc
	v_mul_lo_u32 v4, v2, v1
	v_add_u32_e32 v2, v4, v2
	v_cmp_ne_u32_e32 vcc, v3, v2
	s_and_saveexec_b64 s[0:1], vcc
	s_xor_b64 s[8:9], exec, s[0:1]
	s_cbranch_execz .LBB0_240
	s_waitcnt lgkmcnt(0)
	buffer_wbl2 sc1
	v_mov_b32_e32 v0, 0x2000
	global_load_dword v0, v0, s[6:7] offset:1024 sc1
	s_add_u32 s18, s6, 0x2400
	s_addc_u32 s19, s7, 0
	s_waitcnt vmcnt(0)
	v_cmp_eq_u32_e32 vcc, v0, v1
	s_and_saveexec_b64 s[10:11], vcc
	s_cbranch_execz .LBB0_239
	s_mov_b32 s0, 1
	s_mov_b64 s[20:21], 0
	v_mov_b32_e32 v0, 0
	s_branch .LBB0_230

; __device__ __forceinline__ unsigned xb_ld(unsigned* p)              { return __hip_atomic_load(p, __ATOMIC_RELAXED, __HIP_MEMORY_SCOPE_AGENT); }
; __device__ __forceinline__ unsigned xb_add(unsigned* p, unsigned v) { return __hip_atomic_fetch_add(p, v, __ATOMIC_RELAXED, __HIP_MEMORY_SCOPE_AGENT); }
; #define XB_SPIN(cond, bar) do { unsigned _sp = 0; while (cond) { __builtin_amdgcn_s_sleep(1); \
;     if ((++_sp & 255u) == 0u) { if (xb_ld(&(bar)[XB_TMO])) break; if (_sp > XB_SPIN_CAP) { atomicAdd(&(bar)[XB_TMO], 1u); break; } } } } while (0)
; __device__ __forceinline__ void xcd_barrier(const XcdBarrier& b) {
;     ...
;         const unsigned old = xb_add(&bar[XB_XSUB(b.x)], 1u);
;         const unsigned gen = old / nloc;
;         if (old + 1u == (gen + 1u) * nloc) {
;             __builtin_amdgcn_fence(__ATOMIC_RELEASE, "agent");
;             asm volatile("s_waitcnt vmcnt(0)" ::: "memory");
;             const unsigned og = xb_add(&bar[XB_TOP], 1u);
;             const unsigned tg = og / nx;
;             if (og + 1u == (tg + 1u) * nx) xb_add(&bar[XB_TOPGEN], 1u);
;             else XB_SPIN(xb_ld(&bar[XB_TOPGEN]) == tg, bar);
;             __builtin_amdgcn_fence(__ATOMIC_ACQUIRE, "agent");
;             xb_add(&bar[XB_XGEN(b.x)], 1u);
;             asm volatile("s_waitcnt vmcnt(0)" ::: "memory");
;         } else {
;             XB_SPIN(xb_ld(&bar[XB_XGEN(b.x)]) == gen, bar);
;             __builtin_amdgcn_fence(__ATOMIC_ACQUIRE, "agent");
;             asm volatile("s_waitcnt vmcnt(0)" ::: "memory");
;         }
.LBB0_457:
	s_or_b64 exec, exec, s[12:13]
	v_cvt_f32_u32_e32 v4, v2
	s_waitcnt vmcnt(0)
	v_readfirstlane_b32 s0, v3
	v_sub_u32_e32 v3, 0, v2
	v_rcp_iflag_f32_e32 v4, v4
	v_add_u32_e32 v5, s0, v1
	v_mul_f32_e32 v4, 0x4f7ffffe, v4
	v_cvt_u32_f32_e32 v4, v4
	v_mul_lo_u32 v1, v3, v4
	v_mul_hi_u32 v1, v4, v1
	v_add_u32_e32 v1, v4, v1
	v_mul_hi_u32 v1, v5, v1
	v_mul_lo_u32 v3, v1, v2
	v_sub_u32_e32 v3, v5, v3
	v_add_u32_e32 v4, 1, v1
	v_cmp_ge_u32_e32 vcc, v3, v2
	s_nop 1
	v_cndmask_b32_e32 v1, v1, v4, vcc
	v_sub_u32_e32 v4, v3, v2
	v_cndmask_b32_e32 v3, v3, v4, vcc
	v_add_u32_e32 v4, 1, v1
	v_cmp_ge_u32_e32 vcc, v3, v2
	v_add_u32_e32 v3, 1, v5
	s_nop 0
	v_cndmask_b32_e32 v1, v1, v4, vcc
	v_mul_lo_u32 v4, v2, v1
	v_add_u32_e32 v2, v4, v2
	v_cmp_ne_u32_e32 vcc, v3, v2
	s_and_saveexec_b64 s[0:1], vcc
	s_xor_b64 s[8:9], exec, s[0:1]
	s_cbranch_execz .LBB0_471
	s_waitcnt lgkmcnt(0)
	buffer_wbl2 sc1
	v_mov_b32_e32 v0, 0x2000
	global_load_dword v0, v0, s[6:7] offset:1024 sc1
	s_add_u32 s18, s6, 0x2400
	s_addc_u32 s19, s7, 0
	s_waitcnt vmcnt(0)
	v_cmp_eq_u32_e32 vcc, v0, v1
	s_and_saveexec_b64 s[12:13], vcc
	s_cbranch_execz .LBB0_470
	s_mov_b32 s0, 1
	s_mov_b64 s[20:21], 0
	v_mov_b32_e32 v0, 0
	s_branch .LBB0_461

; __device__ __forceinline__ unsigned xb_ld(unsigned* p)              { return __hip_atomic_load(p, __ATOMIC_RELAXED, __HIP_MEMORY_SCOPE_AGENT); }
; __device__ __forceinline__ unsigned xb_add(unsigned* p, unsigned v) { return __hip_atomic_fetch_add(p, v, __ATOMIC_RELAXED, __HIP_MEMORY_SCOPE_AGENT); }
; #define XB_SPIN(cond, bar) do { unsigned _sp = 0; while (cond) { __builtin_amdgcn_s_sleep(1); \
;     if ((++_sp & 255u) == 0u) { if (xb_ld(&(bar)[XB_TMO])) break; if (_sp > XB_SPIN_CAP) { atomicAdd(&(bar)[XB_TMO], 1u); break; } } } } while (0)
; __device__ __forceinline__ void xcd_barrier(const XcdBarrier& b) {
;     ...
;         const unsigned old = xb_add(&bar[XB_XSUB(b.x)], 1u);
;         const unsigned gen = old / nloc;
;         if (old + 1u == (gen + 1u) * nloc) {
;             __builtin_amdgcn_fence(__ATOMIC_RELEASE, "agent");
;             asm volatile("s_waitcnt vmcnt(0)" ::: "memory");
;             const unsigned og = xb_add(&bar[XB_TOP], 1u);
;             const unsigned tg = og / nx;
;             if (og + 1u == (tg + 1u) * nx) xb_add(&bar[XB_TOPGEN], 1u);
;             else XB_SPIN(xb_ld(&bar[XB_TOPGEN]) == tg, bar);
;             __builtin_amdgcn_fence(__ATOMIC_ACQUIRE, "agent");
;             xb_add(&bar[XB_XGEN(b.x)], 1u);
;             asm volatile("s_waitcnt vmcnt(0)" ::: "memory");
;         } else {
;             XB_SPIN(xb_ld(&bar[XB_XGEN(b.x)]) == gen, bar);
;             __builtin_amdgcn_fence(__ATOMIC_ACQUIRE, "agent");
;             asm volatile("s_waitcnt vmcnt(0)" ::: "memory");
;         }
.LBB0_512:
	s_or_b64 exec, exec, s[14:15]
	v_cvt_f32_u32_e32 v4, v2
	s_waitcnt vmcnt(0)
	v_readfirstlane_b32 s0, v3
	v_sub_u32_e32 v3, 0, v2
	v_rcp_iflag_f32_e32 v4, v4
	v_add_u32_e32 v5, s0, v1
	v_mul_f32_e32 v4, 0x4f7ffffe, v4
	v_cvt_u32_f32_e32 v4, v4
	v_mul_lo_u32 v1, v3, v4
	v_mul_hi_u32 v1, v4, v1
	v_add_u32_e32 v1, v4, v1
	v_mul_hi_u32 v1, v5, v1
	v_mul_lo_u32 v3, v1, v2
	v_sub_u32_e32 v3, v5, v3
	v_add_u32_e32 v4, 1, v1
	v_cmp_ge_u32_e32 vcc, v3, v2
	s_nop 1
	v_cndmask_b32_e32 v1, v1, v4, vcc
	v_sub_u32_e32 v4, v3, v2
	v_cndmask_b32_e32 v3, v3, v4, vcc
	v_add_u32_e32 v4, 1, v1
	v_cmp_ge_u32_e32 vcc, v3, v2
	v_add_u32_e32 v3, 1, v5
	s_nop 0
	v_cndmask_b32_e32 v1, v1, v4, vcc
	v_mul_lo_u32 v4, v2, v1
	v_add_u32_e32 v2, v4, v2
	v_cmp_ne_u32_e32 vcc, v3, v2
	s_and_saveexec_b64 s[0:1], vcc
	s_xor_b64 s[12:13], exec, s[0:1]
	s_cbranch_execz .LBB0_526
	s_waitcnt lgkmcnt(0)
	buffer_wbl2 sc1
	v_mov_b32_e32 v0, 0x2000
	global_load_dword v0, v0, s[8:9] offset:1024 sc1
	s_add_u32 s18, s8, 0x2400
	s_addc_u32 s19, s9, 0
	s_waitcnt vmcnt(0)
	v_cmp_eq_u32_e32 vcc, v0, v1
	s_and_saveexec_b64 s[14:15], vcc
	s_cbranch_execz .LBB0_525
	s_mov_b32 s0, 1
	s_mov_b64 s[20:21], 0
	v_mov_b32_e32 v0, 0
	s_branch .LBB0_516

; __device__ __forceinline__ unsigned xb_ld(unsigned* p)              { return __hip_atomic_load(p, __ATOMIC_RELAXED, __HIP_MEMORY_SCOPE_AGENT); }
; __device__ __forceinline__ unsigned xb_add(unsigned* p, unsigned v) { return __hip_atomic_fetch_add(p, v, __ATOMIC_RELAXED, __HIP_MEMORY_SCOPE_AGENT); }
; #define XB_SPIN(cond, bar) do { unsigned _sp = 0; while (cond) { __builtin_amdgcn_s_sleep(1); \
;     if ((++_sp & 255u) == 0u) { if (xb_ld(&(bar)[XB_TMO])) break; if (_sp > XB_SPIN_CAP) { atomicAdd(&(bar)[XB_TMO], 1u); break; } } } } while (0)
; __device__ __forceinline__ void xcd_barrier(const XcdBarrier& b) {
;     ...
;         const unsigned old = xb_add(&bar[XB_XSUB(b.x)], 1u);
;         const unsigned gen = old / nloc;
;         if (old + 1u == (gen + 1u) * nloc) {
;             __builtin_amdgcn_fence(__ATOMIC_RELEASE, "agent");
;             asm volatile("s_waitcnt vmcnt(0)" ::: "memory");
;             const unsigned og = xb_add(&bar[XB_TOP], 1u);
;             const unsigned tg = og / nx;
;             if (og + 1u == (tg + 1u) * nx) xb_add(&bar[XB_TOPGEN], 1u);
;             else XB_SPIN(xb_ld(&bar[XB_TOPGEN]) == tg, bar);
;             __builtin_amdgcn_fence(__ATOMIC_ACQUIRE, "agent");
;             xb_add(&bar[XB_XGEN(b.x)], 1u);
;             asm volatile("s_waitcnt vmcnt(0)" ::: "memory");
;         } else {
;             XB_SPIN(xb_ld(&bar[XB_XGEN(b.x)]) == gen, bar);
;             __builtin_amdgcn_fence(__ATOMIC_ACQUIRE, "agent");
;             asm volatile("s_waitcnt vmcnt(0)" ::: "memory");
;         }
.LBB0_777:
	s_or_b64 exec, exec, s[14:15]
	v_cvt_f32_u32_e32 v4, v2
	s_waitcnt vmcnt(0)
	v_readfirstlane_b32 s0, v3
	v_sub_u32_e32 v3, 0, v2
	v_rcp_iflag_f32_e32 v4, v4
	v_add_u32_e32 v5, s0, v1
	v_mul_f32_e32 v4, 0x4f7ffffe, v4
	v_cvt_u32_f32_e32 v4, v4
	v_mul_lo_u32 v1, v3, v4
	v_mul_hi_u32 v1, v4, v1
	v_add_u32_e32 v1, v4, v1
	v_mul_hi_u32 v1, v5, v1
	v_mul_lo_u32 v3, v1, v2
	v_sub_u32_e32 v3, v5, v3
	v_add_u32_e32 v4, 1, v1
	v_cmp_ge_u32_e32 vcc, v3, v2
	s_nop 1
	v_cndmask_b32_e32 v1, v1, v4, vcc
	v_sub_u32_e32 v4, v3, v2
	v_cndmask_b32_e32 v3, v3, v4, vcc
	v_add_u32_e32 v4, 1, v1
	v_cmp_ge_u32_e32 vcc, v3, v2
	v_add_u32_e32 v3, 1, v5
	s_nop 0
	v_cndmask_b32_e32 v1, v1, v4, vcc
	v_mul_lo_u32 v4, v2, v1
	v_add_u32_e32 v2, v4, v2
	v_cmp_ne_u32_e32 vcc, v3, v2
	s_and_saveexec_b64 s[0:1], vcc
	s_xor_b64 s[12:13], exec, s[0:1]
	s_cbranch_execz .LBB0_791
	s_waitcnt lgkmcnt(0)
	buffer_wbl2 sc1
	v_mov_b32_e32 v0, 0x2000
	global_load_dword v0, v0, s[8:9] offset:1024 sc1
	s_add_u32 s16, s8, 0x2400
	s_addc_u32 s17, s9, 0
	s_waitcnt vmcnt(0)
	v_cmp_eq_u32_e32 vcc, v0, v1
	s_and_saveexec_b64 s[14:15], vcc
	s_cbranch_execz .LBB0_790
	s_mov_b32 s0, 1
	s_mov_b64 s[18:19], 0
	v_mov_b32_e32 v0, 0
	s_branch .LBB0_781

; __device__ __forceinline__ unsigned xb_ld(unsigned* p)              { return __hip_atomic_load(p, __ATOMIC_RELAXED, __HIP_MEMORY_SCOPE_AGENT); }
; __device__ __forceinline__ unsigned xb_add(unsigned* p, unsigned v) { return __hip_atomic_fetch_add(p, v, __ATOMIC_RELAXED, __HIP_MEMORY_SCOPE_AGENT); }
; #define XB_SPIN(cond, bar) do { unsigned _sp = 0; while (cond) { __builtin_amdgcn_s_sleep(1); \
;     if ((++_sp & 255u) == 0u) { if (xb_ld(&(bar)[XB_TMO])) break; if (_sp > XB_SPIN_CAP) { atomicAdd(&(bar)[XB_TMO], 1u); break; } } } } while (0)
; __device__ __forceinline__ void xcd_barrier(const XcdBarrier& b) {
;     ...
;         const unsigned old = xb_add(&bar[XB_XSUB(b.x)], 1u);
;         const unsigned gen = old / nloc;
;         if (old + 1u == (gen + 1u) * nloc) {
;             __builtin_amdgcn_fence(__ATOMIC_RELEASE, "agent");
;             asm volatile("s_waitcnt vmcnt(0)" ::: "memory");
;             const unsigned og = xb_add(&bar[XB_TOP], 1u);
;             const unsigned tg = og / nx;
;             if (og + 1u == (tg + 1u) * nx) xb_add(&bar[XB_TOPGEN], 1u);
;             else XB_SPIN(xb_ld(&bar[XB_TOPGEN]) == tg, bar);
;             __builtin_amdgcn_fence(__ATOMIC_ACQUIRE, "agent");
;             xb_add(&bar[XB_XGEN(b.x)], 1u);
;             asm volatile("s_waitcnt vmcnt(0)" ::: "memory");
;         } else {
;             XB_SPIN(xb_ld(&bar[XB_XGEN(b.x)]) == gen, bar);
;             __builtin_amdgcn_fence(__ATOMIC_ACQUIRE, "agent");
;             asm volatile("s_waitcnt vmcnt(0)" ::: "memory");
;         }
.LBB0_921:
	s_or_b64 exec, exec, s[8:9]
	v_cvt_f32_u32_e32 v4, v2
	s_waitcnt vmcnt(0)
	v_readfirstlane_b32 s6, v3
	v_sub_u32_e32 v3, 0, v2
	v_rcp_iflag_f32_e32 v4, v4
	v_add_u32_e32 v5, s6, v1
	v_mul_f32_e32 v4, 0x4f7ffffe, v4
	v_cvt_u32_f32_e32 v4, v4
	v_mul_lo_u32 v1, v3, v4
	v_mul_hi_u32 v1, v4, v1
	v_add_u32_e32 v1, v4, v1
	v_mul_hi_u32 v1, v5, v1
	v_mul_lo_u32 v3, v1, v2
	v_sub_u32_e32 v3, v5, v3
	v_add_u32_e32 v4, 1, v1
	v_cmp_ge_u32_e32 vcc, v3, v2
	s_nop 1
	v_cndmask_b32_e32 v1, v1, v4, vcc
	v_sub_u32_e32 v4, v3, v2
	v_cndmask_b32_e32 v3, v3, v4, vcc
	v_add_u32_e32 v4, 1, v1
	v_cmp_ge_u32_e32 vcc, v3, v2
	v_add_u32_e32 v3, 1, v5
	s_nop 0
	v_cndmask_b32_e32 v1, v1, v4, vcc
	v_mul_lo_u32 v4, v2, v1
	v_add_u32_e32 v2, v4, v2
	v_cmp_ne_u32_e32 vcc, v3, v2
	s_and_saveexec_b64 s[6:7], vcc
	s_xor_b64 s[6:7], exec, s[6:7]
	s_cbranch_execz .LBB0_935
	s_waitcnt lgkmcnt(0)
	buffer_wbl2 sc1
	v_mov_b32_e32 v0, 0x2000
	global_load_dword v0, v0, s[0:1] offset:1024 sc1
	s_add_u32 s10, s0, 0x2400
	s_addc_u32 s11, s1, 0
	s_waitcnt vmcnt(0)
	v_cmp_eq_u32_e32 vcc, v0, v1
	s_and_saveexec_b64 s[8:9], vcc
	s_cbranch_execz .LBB0_934
	s_mov_b32 s22, 1
	s_mov_b64 s[12:13], 0
	v_mov_b32_e32 v0, 0
	s_branch .LBB0_925
